# NSA window slow path: next-tile index via v_min_i32 as in the fast path
# baseline (speedup 1.0000x reference)
; #define SB0 __builtin_amdgcn_sched_barrier(0)
; template <class MaskF>
; __device__ __forceinline__ void qk64(const bf16x8 (&kq)[8], const bf16x8 (&qf)[2], float scale, MaskF maskf, int lane,
;                                      f32x4 (&st)[4]) {
;   const int q = lane >> 4;
; #pragma unroll
;   for (int kt = 0; kt < 4; ++kt) {
;     f32x4 z = {0.f, 0.f, 0.f, 0.f};
;     z = mfma16(kq[2 * kt], qf[0], z);
;     z = mfma16(kq[2 * kt + 1], qf[1], z);
; #pragma unroll
;     for (int r = 0; r < 4; ++r) st[kt][r] = maskf(kt * 16 + q * 4 + r) ? z[r] * scale : -INFINITY;
;   }
; }
; __device__ __forceinline__ void phase_nsa_attn(const Params& p, char* smem, volatile LAS unsigned* vb_) {
;     ...
;       for (int i = 0; i < ntile; ++i) {
;         const int k0 = lo + i * 64;
;         const int kx = lo + (i + 1 < ntile ? i + 1 : i) * 64;
;         f32x4 st[4];
;         qk64(kA, qf, scale, [&](int ko) { const int ks = k0 + ko; return (ks <= s) && (ks + 512 > s); }, lane, st);
;         SB0;
;         k_load64(kA, Kw + (size_t)kx * 64, lane);
;         SB0;
;         softmax_update(st, m, lsum, o);
.Lnw_slow:
	s_waitcnt vmcnt(15)
	v_mfma_f32_16x16x32_bf16 v[88:91], v[88:91], v[4:7], 0
	s_add_i32 s22, s11, 1
	v_min_i32_e32 v2, s22, v93
	s_waitcnt vmcnt(14)
	v_mfma_f32_16x16x32_bf16 v[84:87], v[84:87], v[8:11], v[88:91]
	s_waitcnt vmcnt(13)
	v_mfma_f32_16x16x32_bf16 v[80:83], v[80:83], v[4:7], 0
	s_waitcnt vmcnt(12)
	v_mfma_f32_16x16x32_bf16 v[76:79], v[76:79], v[8:11], v[80:83]
	s_waitcnt vmcnt(11)
	v_mfma_f32_16x16x32_bf16 v[72:75], v[72:75], v[4:7], 0
	s_waitcnt vmcnt(10)
	v_mfma_f32_16x16x32_bf16 v[68:71], v[68:71], v[8:11], v[72:75]
	s_waitcnt vmcnt(9)
	v_mfma_f32_16x16x32_bf16 v[52:55], v[52:55], v[4:7], 0
	s_waitcnt vmcnt(8)
	v_mfma_f32_16x16x32_bf16 v[44:47], v[44:47], v[8:11], v[52:55]
	v_mov_b32_e32 v92, v98
	v_lshl_add_u32 v2, v2, 6, v0
	v_add_u32_e32 v3, v94, v95
	s_movk_i32 s98, 0x200
	v_sub_u32_e32 v88, v155, v3
	v_mov_b32_e32 v72, v88
	v_add_u32_e32 v73, -1, v88
	v_cmp_gt_u32_e32 vcc, s98, v72
	v_cmp_gt_u32_e64 s[0:1], s98, v73
	v_mul_f32_e32 v74, 0x3e38aa3b, v84
	v_mul_f32_e32 v75, 0x3e38aa3b, v85
	v_cndmask_b32_e32 v99, v203, v74, vcc
	v_cndmask_b32_e64 v100, v203, v75, s[0:1]
	v_add_u32_e32 v72, -2, v88
	v_add_u32_e32 v73, -3, v88
	v_cmp_gt_u32_e32 vcc, s98, v72
	v_cmp_gt_u32_e64 s[0:1], s98, v73
	v_mul_f32_e32 v74, 0x3e38aa3b, v86
	v_mul_f32_e32 v75, 0x3e38aa3b, v87
	v_cndmask_b32_e32 v101, v203, v74, vcc
	v_cndmask_b32_e64 v102, v203, v75, s[0:1]
	v_add_u32_e32 v72, -16, v88
	v_add_u32_e32 v73, -17, v88
	v_cmp_gt_u32_e32 vcc, s98, v72
	v_cmp_gt_u32_e64 s[0:1], s98, v73
	v_mul_f32_e32 v74, 0x3e38aa3b, v76
	v_mul_f32_e32 v75, 0x3e38aa3b, v77
	v_cndmask_b32_e32 v103, v203, v74, vcc
	v_cndmask_b32_e64 v104, v203, v75, s[0:1]
	v_add_u32_e32 v72, -18, v88
	v_add_u32_e32 v73, -19, v88
	v_cmp_gt_u32_e32 vcc, s98, v72
	v_cmp_gt_u32_e64 s[0:1], s98, v73
	v_mul_f32_e32 v74, 0x3e38aa3b, v78
	v_mul_f32_e32 v75, 0x3e38aa3b, v79
	v_cndmask_b32_e32 v105, v203, v74, vcc
	v_cndmask_b32_e64 v106, v203, v75, s[0:1]
	v_add_u32_e32 v72, -32, v88
	v_add_u32_e32 v73, -33, v88
	v_cmp_gt_u32_e32 vcc, s98, v72
	v_cmp_gt_u32_e64 s[0:1], s98, v73
	v_mul_f32_e32 v74, 0x3e38aa3b, v68
	v_mul_f32_e32 v75, 0x3e38aa3b, v69
	v_cndmask_b32_e32 v107, v203, v74, vcc
	v_cndmask_b32_e64 v108, v203, v75, s[0:1]
	v_add_u32_e32 v72, -34, v88
	v_add_u32_e32 v73, -35, v88
	v_cmp_gt_u32_e32 vcc, s98, v72
	v_cmp_gt_u32_e64 s[0:1], s98, v73
	v_mul_f32_e32 v74, 0x3e38aa3b, v70
	v_mul_f32_e32 v75, 0x3e38aa3b, v71
	v_cndmask_b32_e32 v109, v203, v74, vcc
	v_cndmask_b32_e64 v110, v203, v75, s[0:1]
	v_add_u32_e32 v72, -48, v88
	v_add_u32_e32 v73, -49, v88
	v_cmp_gt_u32_e32 vcc, s98, v72
	v_cmp_gt_u32_e64 s[0:1], s98, v73
	v_mul_f32_e32 v74, 0x3e38aa3b, v44
	v_mul_f32_e32 v75, 0x3e38aa3b, v45
	v_cndmask_b32_e32 v111, v203, v74, vcc
	v_cndmask_b32_e64 v112, v203, v75, s[0:1]
	v_add_u32_e32 v72, -50, v88
	v_add_u32_e32 v73, -51, v88
	v_cmp_gt_u32_e32 vcc, s98, v72
	v_cmp_gt_u32_e64 s[0:1], s98, v73
	v_mul_f32_e32 v74, 0x3e38aa3b, v46
	v_mul_f32_e32 v75, 0x3e38aa3b, v47
	v_cndmask_b32_e32 v113, v203, v74, vcc
	v_cndmask_b32_e64 v114, v203, v75, s[0:1]
	v_ashrrev_i32_e32 v3, 31, v2
	v_lshlrev_b64 v[44:45], 7, v[2:3]
	v_lshl_add_u64 v[44:45], v[142:143], 0, v[44:45]
	global_load_dwordx4 v[88:91], v[44:45], off
	global_load_dwordx4 v[84:87], v[44:45], off offset:1024
	global_load_dwordx4 v[80:83], v[44:45], off offset:2048
	global_load_dwordx4 v[76:79], v[44:45], off offset:3072
	v_add_co_u32_e32 v44, vcc, s33, v44
	s_nop 1
	v_addc_co_u32_e32 v45, vcc, 0, v45, vcc
	global_load_dwordx4 v[72:75], v[44:45], off
	global_load_dwordx4 v[68:71], v[44:45], off offset:1024
	global_load_dwordx4 v[52:55], v[44:45], off offset:2048
	s_nop 0
	global_load_dwordx4 v[44:47], v[44:45], off offset:3072
	v_max3_f32 v98, v99, s3, v100
	v_max3_f32 v98, v98, v101, v102
	v_max3_f32 v98, v98, v103, v104
	v_max3_f32 v98, v98, v105, v106
	v_max3_f32 v98, v98, v107, v108
	v_max3_f32 v98, v98, v109, v110
	v_max3_f32 v98, v98, v111, v112
	v_max3_f32 v98, v98, v113, v114
	v_mov_b32_e32 v115, v98
	s_nop 1
	v_permlane16_swap_b32_e32 v115, v98
	v_max_f32_e32 v98, v98, v115
	v_mov_b32_e32 v115, v98
	s_nop 1
	v_permlane32_swap_b32_e32 v115, v98
	v_max3_f32 v98, v92, v98, v115
	v_sub_f32_e32 v92, v92, v98
	v_exp_f32_e32 v92, v92
	s_nop 0
	v_cmp_neq_f32_e32 vcc, 1.0, v92
	s_cbranch_vccz .LBB0_102
	v_pk_mul_f32 v[26:27], v[26:27], v[92:93] op_sel_hi:[1,0]
	v_pk_mul_f32 v[24:25], v[24:25], v[92:93] op_sel_hi:[1,0]
	v_pk_mul_f32 v[22:23], v[22:23], v[92:93] op_sel_hi:[1,0]
	v_pk_mul_f32 v[20:21], v[20:21], v[92:93] op_sel_hi:[1,0]
	v_pk_mul_f32 v[18:19], v[18:19], v[92:93] op_sel_hi:[1,0]
	v_pk_mul_f32 v[16:17], v[16:17], v[92:93] op_sel_hi:[1,0]
	v_pk_mul_f32 v[14:15], v[14:15], v[92:93] op_sel_hi:[1,0]
	v_pk_mul_f32 v[12:13], v[12:13], v[92:93] op_sel_hi:[1,0]
	s_branch .LBB0_102
